# v011
# speedup vs baseline: 1.0117x; 1.0035x over previous
; __device__ __forceinline__ float lo16(unsigned u) { return __uint_as_float(u << 16); }
; __device__ __forceinline__ float hi16(unsigned u) { return __uint_as_float(u & 0xffff0000u); }
; __device__ __forceinline__ float sigm(float x) { return __builtin_amdgcn_rcpf(1.f + __expf(-x)); }
; #define SCHED __builtin_amdgcn_sched_barrier(0)
; __device__ __forceinline__ uint2 pack4(f32x4 a) { uint2 w; w.x = pack2(a[0], a[1]); w.y = pack2(a[2], a[3]); return w; }
; __global__ void __launch_bounds__(512) mega(Params p) {
;     ...
;           int d0 = (bcol >> 2) + wc * 16 + fq * 4;
; #pragma unroll
;           for (int ai = 0; ai < 2; ++ai) {
;             size_t rbase = (size_t)(brow + ai * 128 + wr * 64 + fr);
;             uint2 yv[4][4];
; #pragma unroll
;             for (int m = 0; m < 4; ++m)
; #pragma unroll
;               for (int br = 0; br < 4; ++br) yv[m][br] = *(const uint2*)(YBR + (rbase + m * 16) * 8192 + br * 2048 + d0);
;             SCHED;
; #pragma unroll
;             for (int m = 0; m < 4; ++m) {
;               f32x4 v = {0.f, 0.f, 0.f, 0.f};
; #pragma unroll
;               for (int bj = 0; bj < 2; ++bj)
; #pragma unroll
;                 for (int n = 0; n < 2; ++n) {
;                   uint2 y = yv[m][bj * 2 + n];
;                   f32x4 a = acc[ai][bj][m][n];
;                   v[0] += sigm(a[0]) * lo16(y.x); v[1] += sigm(a[1]) * hi16(y.x);
;                   v[2] += sigm(a[2]) * lo16(y.y); v[3] += sigm(a[3]) * hi16(y.y);
;                 }
;               *(uint2*)(MG + (rbase + m * 16) * 2048 + d0) = pack4(v);
.LBB0_2513:
	s_ashr_i32 s2, s18, 2
	v_ashrrev_i32_e32 v129, 2, v162
	v_lshrrev_b32_e32 v128, 2, v162
	v_and_b32_e32 v129, 0xffffffc0, v129
	v_and_or_b32 v128, v128, 60, s2
	v_add_u32_e32 v129, s14, v129
	v_and_or_b32 v132, v162, 15, v129
	v_ashrrev_i32_e32 v129, 31, v128
	v_lshlrev_b64 v[128:129], 1, v[128:129]
	v_ashrrev_i32_e32 v133, 31, v132
	v_lshl_add_u64 v[130:131], s[6:7], 0, v[128:129]
	v_lshlrev_b64 v[134:135], 14, v[132:133]
	v_lshl_add_u64 v[134:135], v[130:131], 0, v[134:135]
	v_add_co_u32_e32 v136, vcc, s42, v134
	s_movk_i32 s2, 0x3000
	s_nop 0
	v_addc_co_u32_e32 v137, vcc, 0, v135, vcc
	v_or_b32_e32 v152, 16, v132
	v_mov_b32_e32 v153, v133
	v_add_co_u32_e32 v138, vcc, s2, v134
	v_lshlrev_b64 v[140:141], 14, v[152:153]
	s_nop 0
	v_addc_co_u32_e32 v139, vcc, 0, v135, vcc
	v_lshl_add_u64 v[140:141], v[130:131], 0, v[140:141]
	v_add_co_u32_e32 v142, vcc, s42, v140
	v_lshl_add_u64 v[128:129], s[8:9], 0, v[128:129]
	s_nop 0
	v_addc_co_u32_e32 v143, vcc, 0, v141, vcc
	global_load_dwordx2 v[164:165], v[136:137], off offset:-4096
	global_load_dwordx2 v[166:167], v[136:137], off
	global_load_dwordx2 v[160:161], v[142:143], off offset:-4096
	global_load_dwordx2 v[158:159], v[142:143], off
	v_add_co_u32_e32 v136, vcc, s2, v140
	v_or_b32_e32 v142, 32, v132
	v_mov_b32_e32 v143, v133
	v_addc_co_u32_e32 v137, vcc, 0, v141, vcc
	global_load_dwordx2 v[168:169], v[134:135], off
	global_load_dwordx2 v[170:171], v[138:139], off
	global_load_dwordx2 v[172:173], v[140:141], off
	global_load_dwordx2 v[156:157], v[136:137], off
	v_lshlrev_b64 v[134:135], 14, v[142:143]
	v_lshl_add_u64 v[136:137], v[130:131], 0, v[134:135]
	v_add_co_u32_e32 v138, vcc, s42, v136
	v_or_b32_e32 v134, 48, v132
	s_nop 0
	v_addc_co_u32_e32 v139, vcc, 0, v137, vcc
	v_mov_b32_e32 v135, v133
	v_add_co_u32_e32 v144, vcc, s2, v136
	v_lshlrev_b64 v[140:141], 14, v[134:135]
	s_nop 0
	v_addc_co_u32_e32 v145, vcc, 0, v137, vcc
	v_lshl_add_u64 v[174:175], v[130:131], 0, v[140:141]
	v_add_co_u32_e32 v146, vcc, s42, v174
	s_nop 1
	v_addc_co_u32_e32 v147, vcc, 0, v175, vcc
	v_add_co_u32_e32 v180, vcc, s2, v174
	global_load_dwordx2 v[150:151], v[138:139], off offset:-4096
	global_load_dwordx2 v[148:149], v[138:139], off
	global_load_dwordx2 v[140:141], v[146:147], off offset:-4096
	s_nop 0
	global_load_dwordx2 v[138:139], v[146:147], off
	v_addc_co_u32_e32 v181, vcc, 0, v175, vcc
	global_load_dwordx2 v[154:155], v[136:137], off
	global_load_dwordx2 v[146:147], v[144:145], off
	s_nop 0
	global_load_dwordx2 v[144:145], v[174:175], off
	global_load_dwordx2 v[136:137], v[180:181], off
	v_add_u32_e32 v210, 0x80, v132
	v_ashrrev_i32_e32 v211, 31, v210
	v_lshlrev_b64 v[182:183], 14, v[210:211]
	v_lshl_add_u64 v[182:183], v[130:131], 0, v[182:183]
	v_add_co_u32_e32 v184, vcc, s42, v182
	v_or_b32_e32 v200, 16, v210
	s_nop 0
	v_addc_co_u32_e32 v185, vcc, 0, v183, vcc
	v_mov_b32_e32 v201, v211
	v_add_co_u32_e32 v186, vcc, s2, v182
	v_lshlrev_b64 v[188:189], 14, v[200:201]
	s_nop 0
	v_addc_co_u32_e32 v187, vcc, 0, v183, vcc
	v_lshl_add_u64 v[188:189], v[130:131], 0, v[188:189]
	v_add_co_u32_e32 v190, vcc, s42, v188
	s_nop 1
	v_addc_co_u32_e32 v191, vcc, 0, v189, vcc
	global_load_dwordx2 v[212:213], v[184:185], off offset:-4096
	global_load_dwordx2 v[214:215], v[184:185], off
	global_load_dwordx2 v[208:209], v[190:191], off offset:-4096
	global_load_dwordx2 v[206:207], v[190:191], off
	v_add_co_u32_e32 v184, vcc, s2, v188
	v_or_b32_e32 v190, 32, v210
	v_mov_b32_e32 v191, v211
	v_addc_co_u32_e32 v185, vcc, 0, v189, vcc
	global_load_dwordx2 v[216:217], v[182:183], off
	global_load_dwordx2 v[218:219], v[186:187], off
	global_load_dwordx2 v[222:223], v[188:189], off
	global_load_dwordx2 v[204:205], v[184:185], off
	v_lshlrev_b64 v[182:183], 14, v[190:191]
	v_lshl_add_u64 v[184:185], v[130:131], 0, v[182:183]
	v_add_co_u32_e32 v186, vcc, s42, v184
	v_or_b32_e32 v182, 48, v210
	s_nop 0
	v_addc_co_u32_e32 v187, vcc, 0, v185, vcc
	v_mov_b32_e32 v183, v211
	v_add_co_u32_e32 v192, vcc, s2, v184
	v_lshlrev_b64 v[188:189], 14, v[182:183]
	s_nop 0
	v_addc_co_u32_e32 v193, vcc, 0, v185, vcc
	v_lshl_add_u64 v[224:225], v[130:131], 0, v[188:189]
	v_add_co_u32_e32 v194, vcc, s42, v224
	s_nop 1
	v_addc_co_u32_e32 v195, vcc, 0, v225, vcc
	v_add_co_u32_e32 v226, vcc, s2, v224
	global_load_dwordx2 v[198:199], v[186:187], off offset:-4096
	global_load_dwordx2 v[196:197], v[186:187], off
	global_load_dwordx2 v[188:189], v[194:195], off offset:-4096
	s_nop 0
	global_load_dwordx2 v[186:187], v[194:195], off
	v_addc_co_u32_e32 v227, vcc, 0, v225, vcc
	global_load_dwordx2 v[202:203], v[184:185], off
	global_load_dwordx2 v[194:195], v[192:193], off
	s_nop 0
	global_load_dwordx2 v[192:193], v[224:225], off
	global_load_dwordx2 v[184:185], v[226:227], off
	v_mul_f32_e32 v124, 0xbfb8aa3b, v124
	v_exp_f32_e32 v124, v124
	v_mul_f32_e32 v126, 0xbfb8aa3b, v126
	v_exp_f32_e32 v126, v126
	v_mul_f32_e32 v127, 0xbfb8aa3b, v127
	v_exp_f32_e32 v127, v127
	v_mul_f32_e32 v120, 0xbfb8aa3b, v120
	v_exp_f32_e32 v120, v120
	v_add_f32_e32 v124, 1.0, v124
	v_rcp_f32_e32 v124, v124
	v_add_f32_e32 v126, 1.0, v126
	v_rcp_f32_e32 v126, v126
	v_add_f32_e32 v127, 1.0, v127
	v_rcp_f32_e32 v127, v127
	v_add_f32_e32 v120, 1.0, v120
	s_waitcnt vmcnt(16)
; __device__ __forceinline__ float lo16(unsigned u) { return __uint_as_float(u << 16); }
; __device__ __forceinline__ float hi16(unsigned u) { return __uint_as_float(u & 0xffff0000u); }
; __device__ __forceinline__ float sigm(float x) { return __builtin_amdgcn_rcpf(1.f + __expf(-x)); }
; __device__ __forceinline__ uint2 pack4(f32x4 a) { uint2 w; w.x = pack2(a[0], a[1]); w.y = pack2(a[2], a[3]); return w; }
; __global__ void __launch_bounds__(512) mega(Params p) {
;     ...
;             for (int m = 0; m < 4; ++m) {
;               f32x4 v = {0.f, 0.f, 0.f, 0.f};
; #pragma unroll
;               for (int bj = 0; bj < 2; ++bj)
; #pragma unroll
;                 for (int n = 0; n < 2; ++n) {
;                   uint2 y = yv[m][bj * 2 + n];
;                   f32x4 a = acc[ai][bj][m][n];
;                   v[0] += sigm(a[0]) * lo16(y.x); v[1] += sigm(a[1]) * hi16(y.x);
;                   v[2] += sigm(a[2]) * lo16(y.y); v[3] += sigm(a[3]) * hi16(y.y);
;                 }
;               *(uint2*)(MG + (rbase + m * 16) * 2048 + d0) = pack4(v);
	v_lshlrev_b32_e32 v163, 16, v168
	v_rcp_f32_e32 v120, v120
	v_fma_f32 v124, v124, v163, 0
	v_lshlrev_b32_e32 v163, 16, v169
	v_mul_f32_e32 v125, 0xbfb8aa3b, v125
	v_fma_f32 v126, v126, v163, 0
	v_and_b32_e32 v163, 0xffff0000, v169
	v_exp_f32_e32 v125, v125
	v_fma_f32 v127, v127, v163, 0
	v_lshlrev_b32_e32 v163, 16, v164
	v_mul_f32_e32 v121, 0xbfb8aa3b, v121
	v_exp_f32_e32 v121, v121
	v_fmac_f32_e32 v124, v120, v163
	v_mul_f32_e32 v120, 0xbfb8aa3b, v122
	v_exp_f32_e32 v120, v120
	v_add_f32_e32 v125, 1.0, v125
	v_rcp_f32_e32 v125, v125
	v_add_f32_e32 v121, 1.0, v121
	v_rcp_f32_e32 v121, v121
	v_add_f32_e32 v120, 1.0, v120
	v_mul_f32_e32 v123, 0xbfb8aa3b, v123
	v_rcp_f32_e32 v120, v120
	v_exp_f32_e32 v123, v123
	v_mul_f32_e32 v116, 0xbfb8aa3b, v116
	v_and_b32_e32 v168, 0xffff0000, v168
	v_exp_f32_e32 v116, v116
	v_mul_f32_e32 v117, 0xbfb8aa3b, v117
	v_fma_f32 v125, v125, v168, 0
	v_and_b32_e32 v122, 0xffff0000, v164
	v_exp_f32_e32 v117, v117
	v_fmac_f32_e32 v125, v121, v122
	v_lshlrev_b32_e32 v121, 16, v165
	v_fmac_f32_e32 v126, v120, v121
	v_add_f32_e32 v120, 1.0, v123
	v_rcp_f32_e32 v120, v120
	v_add_f32_e32 v116, 1.0, v116
	v_rcp_f32_e32 v116, v116
	v_add_f32_e32 v117, 1.0, v117
	v_mul_f32_e32 v118, 0xbfb8aa3b, v118
	v_rcp_f32_e32 v117, v117
	v_exp_f32_e32 v118, v118
	v_and_b32_e32 v121, 0xffff0000, v165
	v_fmac_f32_e32 v127, v120, v121
	v_lshlrev_b32_e32 v120, 16, v166
	v_fmac_f32_e32 v124, v116, v120
	v_and_b32_e32 v116, 0xffff0000, v166
	v_fmac_f32_e32 v125, v117, v116
	v_add_f32_e32 v116, 1.0, v118
	v_mul_f32_e32 v118, 0xbfb8aa3b, v119
	v_rcp_f32_e32 v116, v116
	v_exp_f32_e32 v118, v118
	v_mul_f32_e32 v112, 0xbfb8aa3b, v112
	v_exp_f32_e32 v112, v112
	v_lshlrev_b32_e32 v117, 16, v167
	v_fmac_f32_e32 v126, v116, v117
	v_add_f32_e32 v116, 1.0, v118
	v_rcp_f32_e32 v116, v116
	v_add_f32_e32 v112, 1.0, v112
	v_mul_f32_e32 v113, 0xbfb8aa3b, v113
	v_rcp_f32_e32 v112, v112
	v_exp_f32_e32 v113, v113
	v_and_b32_e32 v117, 0xffff0000, v167
	v_fmac_f32_e32 v127, v116, v117
	v_lshlrev_b32_e32 v116, 16, v170
	v_fmac_f32_e32 v124, v112, v116
	v_add_f32_e32 v112, 1.0, v113
	v_mul_f32_e32 v114, 0xbfb8aa3b, v114
	v_rcp_f32_e32 v112, v112
	v_exp_f32_e32 v114, v114
	v_mul_f32_e32 v115, 0xbfb8aa3b, v115
	v_exp_f32_e32 v115, v115
	v_and_b32_e32 v113, 0xffff0000, v170
	v_mul_f32_e32 v108, 0xbfb8aa3b, v108
	v_fmac_f32_e32 v125, v112, v113
	v_add_f32_e32 v112, 1.0, v114
	v_exp_f32_e32 v108, v108
	v_mul_f32_e32 v109, 0xbfb8aa3b, v109
	v_rcp_f32_e32 v112, v112
	v_add_f32_e32 v113, 1.0, v115
	v_exp_f32_e32 v109, v109
	v_mul_f32_e32 v110, 0xbfb8aa3b, v110
	v_rcp_f32_e32 v113, v113
	v_exp_f32_e32 v110, v110
	v_mul_f32_e32 v111, 0xbfb8aa3b, v111
	v_exp_f32_e32 v111, v111
	v_mul_f32_e32 v104, 0xbfb8aa3b, v104
	v_lshlrev_b32_e32 v114, 16, v171
	v_add_f32_e32 v108, 1.0, v108
	v_exp_f32_e32 v104, v104
	v_fmac_f32_e32 v126, v112, v114
	v_and_b32_e32 v112, 0xffff0000, v171
	v_rcp_f32_e32 v108, v108
	v_add_f32_e32 v109, 1.0, v109
	v_fmac_f32_e32 v127, v113, v112
	v_lshlrev_b64 v[114:115], 12, v[132:133]
	v_rcp_f32_e32 v109, v109
	v_add_f32_e32 v110, 1.0, v110
	v_cvt_pk_bf16_f32 v112, v124, v125
	v_cvt_pk_bf16_f32 v113, v126, v127
	v_lshl_add_u64 v[114:115], v[128:129], 0, v[114:115]
	v_rcp_f32_e32 v110, v110
	v_add_f32_e32 v111, 1.0, v111
	global_store_dwordx2 v[114:115], v[112:113], off
	v_lshlrev_b32_e32 v112, 16, v172
	v_rcp_f32_e32 v111, v111
	v_add_f32_e32 v104, 1.0, v104
	v_fma_f32 v108, v108, v112, 0
	v_and_b32_e32 v112, 0xffff0000, v172
	v_rcp_f32_e32 v104, v104
	v_fma_f32 v109, v109, v112, 0
	v_lshlrev_b32_e32 v112, 16, v173
	v_fma_f32 v110, v110, v112, 0
	v_and_b32_e32 v112, 0xffff0000, v173
	v_fma_f32 v111, v111, v112, 0
	v_lshlrev_b32_e32 v112, 16, v160
	v_mul_f32_e32 v105, 0xbfb8aa3b, v105
	v_exp_f32_e32 v105, v105
	v_fmac_f32_e32 v108, v104, v112
	v_mul_f32_e32 v104, 0xbfb8aa3b, v106
	v_exp_f32_e32 v104, v104
	v_add_f32_e32 v105, 1.0, v105
	v_rcp_f32_e32 v105, v105
	v_mul_f32_e32 v107, 0xbfb8aa3b, v107
	v_add_f32_e32 v104, 1.0, v104
	v_rcp_f32_e32 v104, v104
	v_exp_f32_e32 v107, v107
	v_mul_f32_e32 v100, 0xbfb8aa3b, v100
	v_exp_f32_e32 v100, v100
	v_mul_f32_e32 v101, 0xbfb8aa3b, v101
	v_and_b32_e32 v106, 0xffff0000, v160
	v_exp_f32_e32 v101, v101
	v_fmac_f32_e32 v109, v105, v106
	v_lshlrev_b32_e32 v105, 16, v161
	v_fmac_f32_e32 v110, v104, v105
	v_add_f32_e32 v104, 1.0, v107
	v_rcp_f32_e32 v104, v104
	v_add_f32_e32 v100, 1.0, v100
	v_rcp_f32_e32 v100, v100
	v_add_f32_e32 v101, 1.0, v101
	v_mul_f32_e32 v102, 0xbfb8aa3b, v102
	v_rcp_f32_e32 v101, v101
	v_exp_f32_e32 v102, v102
	v_and_b32_e32 v105, 0xffff0000, v161
	v_fmac_f32_e32 v111, v104, v105
	v_lshlrev_b32_e32 v104, 16, v158
	v_fmac_f32_e32 v108, v100, v104
	v_and_b32_e32 v100, 0xffff0000, v158
	v_fmac_f32_e32 v109, v101, v100
	v_add_f32_e32 v100, 1.0, v102
	v_mul_f32_e32 v102, 0xbfb8aa3b, v103
	v_rcp_f32_e32 v100, v100
	v_exp_f32_e32 v102, v102
	v_mul_f32_e32 v96, 0xbfb8aa3b, v96
	v_exp_f32_e32 v96, v96
	v_lshlrev_b32_e32 v101, 16, v159
	v_fmac_f32_e32 v110, v100, v101
	v_add_f32_e32 v100, 1.0, v102
	v_rcp_f32_e32 v100, v100
	v_add_f32_e32 v96, 1.0, v96
	v_mul_f32_e32 v97, 0xbfb8aa3b, v97
	v_rcp_f32_e32 v96, v96
	v_exp_f32_e32 v97, v97
	v_and_b32_e32 v101, 0xffff0000, v159
	v_fmac_f32_e32 v111, v100, v101
	v_lshlrev_b32_e32 v100, 16, v156
	v_fmac_f32_e32 v108, v96, v100
	v_add_f32_e32 v96, 1.0, v97
	v_mul_f32_e32 v98, 0xbfb8aa3b, v98
	v_rcp_f32_e32 v96, v96
	v_exp_f32_e32 v98, v98
	v_mul_f32_e32 v99, 0xbfb8aa3b, v99
	v_exp_f32_e32 v99, v99
	v_and_b32_e32 v97, 0xffff0000, v156
	v_mul_f32_e32 v92, 0xbfb8aa3b, v92
	v_fmac_f32_e32 v109, v96, v97
	v_add_f32_e32 v96, 1.0, v98
	v_exp_f32_e32 v92, v92
; __device__ __forceinline__ float lo16(unsigned u) { return __uint_as_float(u << 16); }
; __device__ __forceinline__ float hi16(unsigned u) { return __uint_as_float(u & 0xffff0000u); }
; __device__ __forceinline__ float sigm(float x) { return __builtin_amdgcn_rcpf(1.f + __expf(-x)); }
; __device__ __forceinline__ uint2 pack4(f32x4 a) { uint2 w; w.x = pack2(a[0], a[1]); w.y = pack2(a[2], a[3]); return w; }
; __global__ void __launch_bounds__(512) mega(Params p) {
;     ...
;             size_t rbase = (size_t)(brow + ai * 128 + wr * 64 + fr);
;             uint2 yv[4][4];
; #pragma unroll
;             for (int m = 0; m < 4; ++m)
; #pragma unroll
;               for (int br = 0; br < 4; ++br) yv[m][br] = *(const uint2*)(YBR + (rbase + m * 16) * 8192 + br * 2048 + d0);
;     ...
;             for (int m = 0; m < 4; ++m) {
;               f32x4 v = {0.f, 0.f, 0.f, 0.f};
; #pragma unroll
;               for (int bj = 0; bj < 2; ++bj)
; #pragma unroll
;                 for (int n = 0; n < 2; ++n) {
;                   uint2 y = yv[m][bj * 2 + n];
;                   f32x4 a = acc[ai][bj][m][n];
;                   v[0] += sigm(a[0]) * lo16(y.x); v[1] += sigm(a[1]) * hi16(y.x);
;                   v[2] += sigm(a[2]) * lo16(y.y); v[3] += sigm(a[3]) * hi16(y.y);
;                 }
;               *(uint2*)(MG + (rbase + m * 16) * 2048 + d0) = pack4(v);
	v_mul_f32_e32 v93, 0xbfb8aa3b, v93
	v_rcp_f32_e32 v96, v96
	v_add_f32_e32 v97, 1.0, v99
	v_exp_f32_e32 v93, v93
	v_mul_f32_e32 v94, 0xbfb8aa3b, v94
	v_rcp_f32_e32 v97, v97
	v_exp_f32_e32 v94, v94
	v_mul_f32_e32 v95, 0xbfb8aa3b, v95
	v_exp_f32_e32 v95, v95
	v_mul_f32_e32 v88, 0xbfb8aa3b, v88
	v_lshlrev_b32_e32 v98, 16, v157
	v_add_f32_e32 v92, 1.0, v92
	v_exp_f32_e32 v88, v88
	v_fmac_f32_e32 v110, v96, v98
	v_and_b32_e32 v96, 0xffff0000, v157
	v_rcp_f32_e32 v92, v92
	v_add_f32_e32 v93, 1.0, v93
	v_fmac_f32_e32 v111, v97, v96
	v_lshlrev_b64 v[98:99], 12, v[152:153]
	v_rcp_f32_e32 v93, v93
	v_add_f32_e32 v94, 1.0, v94
	v_cvt_pk_bf16_f32 v96, v108, v109
	v_cvt_pk_bf16_f32 v97, v110, v111
	v_lshl_add_u64 v[98:99], v[128:129], 0, v[98:99]
	v_rcp_f32_e32 v94, v94
	v_add_f32_e32 v95, 1.0, v95
	global_store_dwordx2 v[98:99], v[96:97], off
	v_lshlrev_b32_e32 v96, 16, v154
	v_rcp_f32_e32 v95, v95
	v_add_f32_e32 v88, 1.0, v88
	v_fma_f32 v92, v92, v96, 0
	v_and_b32_e32 v96, 0xffff0000, v154
	v_rcp_f32_e32 v88, v88
	v_fma_f32 v93, v93, v96, 0
	v_lshlrev_b32_e32 v96, 16, v155
	v_fma_f32 v94, v94, v96, 0
	v_and_b32_e32 v96, 0xffff0000, v155
	v_fma_f32 v95, v95, v96, 0
	v_lshlrev_b32_e32 v96, 16, v150
	v_mul_f32_e32 v89, 0xbfb8aa3b, v89
	v_exp_f32_e32 v89, v89
	v_fmac_f32_e32 v92, v88, v96
	v_mul_f32_e32 v88, 0xbfb8aa3b, v90
	v_exp_f32_e32 v88, v88
	v_add_f32_e32 v89, 1.0, v89
	v_rcp_f32_e32 v89, v89
	v_mul_f32_e32 v91, 0xbfb8aa3b, v91
	v_add_f32_e32 v88, 1.0, v88
	v_rcp_f32_e32 v88, v88
	v_exp_f32_e32 v91, v91
	v_mul_f32_e32 v84, 0xbfb8aa3b, v84
	v_exp_f32_e32 v84, v84
	v_mul_f32_e32 v85, 0xbfb8aa3b, v85
	v_and_b32_e32 v90, 0xffff0000, v150
	v_exp_f32_e32 v85, v85
	v_fmac_f32_e32 v93, v89, v90
	v_lshlrev_b32_e32 v89, 16, v151
	v_fmac_f32_e32 v94, v88, v89
	v_add_f32_e32 v88, 1.0, v91
	v_rcp_f32_e32 v88, v88
	v_add_f32_e32 v84, 1.0, v84
	v_rcp_f32_e32 v84, v84
	v_add_f32_e32 v85, 1.0, v85
	v_mul_f32_e32 v86, 0xbfb8aa3b, v86
	v_rcp_f32_e32 v85, v85
	v_exp_f32_e32 v86, v86
	v_and_b32_e32 v89, 0xffff0000, v151
	v_fmac_f32_e32 v95, v88, v89
	v_lshlrev_b32_e32 v88, 16, v148
	v_fmac_f32_e32 v92, v84, v88
	v_and_b32_e32 v84, 0xffff0000, v148
	v_fmac_f32_e32 v93, v85, v84
	v_add_f32_e32 v84, 1.0, v86
	v_mul_f32_e32 v86, 0xbfb8aa3b, v87
	v_rcp_f32_e32 v84, v84
	v_exp_f32_e32 v86, v86
	v_mul_f32_e32 v80, 0xbfb8aa3b, v80
	v_exp_f32_e32 v80, v80
	v_lshlrev_b32_e32 v85, 16, v149
	v_fmac_f32_e32 v94, v84, v85
	v_add_f32_e32 v84, 1.0, v86
	v_rcp_f32_e32 v84, v84
	v_add_f32_e32 v80, 1.0, v80
	v_mul_f32_e32 v81, 0xbfb8aa3b, v81
	v_rcp_f32_e32 v80, v80
	v_exp_f32_e32 v81, v81
	v_and_b32_e32 v85, 0xffff0000, v149
	v_fmac_f32_e32 v95, v84, v85
	v_lshlrev_b32_e32 v84, 16, v146
	v_fmac_f32_e32 v92, v80, v84
	v_add_f32_e32 v80, 1.0, v81
	v_mul_f32_e32 v82, 0xbfb8aa3b, v82
	v_rcp_f32_e32 v80, v80
	v_exp_f32_e32 v82, v82
	v_mul_f32_e32 v83, 0xbfb8aa3b, v83
	v_exp_f32_e32 v83, v83
	v_and_b32_e32 v81, 0xffff0000, v146
	v_mul_f32_e32 v76, 0xbfb8aa3b, v76
	v_fmac_f32_e32 v93, v80, v81
	v_add_f32_e32 v80, 1.0, v82
	v_exp_f32_e32 v76, v76
	v_mul_f32_e32 v77, 0xbfb8aa3b, v77
	v_rcp_f32_e32 v80, v80
	v_add_f32_e32 v81, 1.0, v83
	v_exp_f32_e32 v77, v77
	v_mul_f32_e32 v78, 0xbfb8aa3b, v78
	v_rcp_f32_e32 v81, v81
	v_exp_f32_e32 v78, v78
	v_mul_f32_e32 v79, 0xbfb8aa3b, v79
	v_exp_f32_e32 v79, v79
	v_mul_f32_e32 v72, 0xbfb8aa3b, v72
	v_lshlrev_b32_e32 v82, 16, v147
	v_add_f32_e32 v76, 1.0, v76
	v_exp_f32_e32 v72, v72
	v_fmac_f32_e32 v94, v80, v82
	v_and_b32_e32 v80, 0xffff0000, v147
	v_rcp_f32_e32 v76, v76
	v_add_f32_e32 v77, 1.0, v77
	v_fmac_f32_e32 v95, v81, v80
	v_lshlrev_b64 v[82:83], 12, v[142:143]
	v_rcp_f32_e32 v77, v77
	v_add_f32_e32 v78, 1.0, v78
	v_cvt_pk_bf16_f32 v80, v92, v93
	v_cvt_pk_bf16_f32 v81, v94, v95
	v_lshl_add_u64 v[82:83], v[128:129], 0, v[82:83]
	v_rcp_f32_e32 v78, v78
	v_add_f32_e32 v79, 1.0, v79
	global_store_dwordx2 v[82:83], v[80:81], off
	v_lshlrev_b32_e32 v80, 16, v144
	v_rcp_f32_e32 v79, v79
	v_add_f32_e32 v72, 1.0, v72
	v_fma_f32 v76, v76, v80, 0
	v_and_b32_e32 v80, 0xffff0000, v144
	v_rcp_f32_e32 v72, v72
	v_fma_f32 v77, v77, v80, 0
	v_lshlrev_b32_e32 v80, 16, v145
	v_fma_f32 v78, v78, v80, 0
	v_and_b32_e32 v80, 0xffff0000, v145
	v_fma_f32 v79, v79, v80, 0
	v_lshlrev_b32_e32 v80, 16, v140
	v_mul_f32_e32 v73, 0xbfb8aa3b, v73
	v_exp_f32_e32 v73, v73
	v_fmac_f32_e32 v76, v72, v80
	v_mul_f32_e32 v72, 0xbfb8aa3b, v74
	v_exp_f32_e32 v72, v72
	v_add_f32_e32 v73, 1.0, v73
	v_rcp_f32_e32 v73, v73
	v_mul_f32_e32 v75, 0xbfb8aa3b, v75
	v_add_f32_e32 v72, 1.0, v72
	v_rcp_f32_e32 v72, v72
	v_exp_f32_e32 v75, v75
	v_mul_f32_e32 v68, 0xbfb8aa3b, v68
	v_exp_f32_e32 v68, v68
	v_mul_f32_e32 v69, 0xbfb8aa3b, v69
	v_and_b32_e32 v74, 0xffff0000, v140
	v_exp_f32_e32 v69, v69
	v_fmac_f32_e32 v77, v73, v74
	v_lshlrev_b32_e32 v73, 16, v141
	v_fmac_f32_e32 v78, v72, v73
	v_add_f32_e32 v72, 1.0, v75
	v_rcp_f32_e32 v72, v72
	v_add_f32_e32 v68, 1.0, v68
	v_rcp_f32_e32 v68, v68
	v_add_f32_e32 v69, 1.0, v69
	v_mul_f32_e32 v70, 0xbfb8aa3b, v70
	v_rcp_f32_e32 v69, v69
	v_exp_f32_e32 v70, v70
	v_and_b32_e32 v73, 0xffff0000, v141
	v_fmac_f32_e32 v79, v72, v73
	v_lshlrev_b32_e32 v72, 16, v138
	v_fmac_f32_e32 v76, v68, v72
	v_and_b32_e32 v68, 0xffff0000, v138
	v_fmac_f32_e32 v77, v69, v68
	v_add_f32_e32 v68, 1.0, v70
	v_mul_f32_e32 v70, 0xbfb8aa3b, v71
	v_rcp_f32_e32 v68, v68
	v_exp_f32_e32 v70, v70
	v_mul_f32_e32 v64, 0xbfb8aa3b, v64
	v_exp_f32_e32 v64, v64
	v_lshlrev_b32_e32 v69, 16, v139
	v_fmac_f32_e32 v78, v68, v69
	v_add_f32_e32 v68, 1.0, v70
	v_rcp_f32_e32 v68, v68
	v_add_f32_e32 v64, 1.0, v64
	v_mul_f32_e32 v65, 0xbfb8aa3b, v65
	v_rcp_f32_e32 v64, v64
	v_exp_f32_e32 v65, v65
	v_and_b32_e32 v69, 0xffff0000, v139
	v_fmac_f32_e32 v79, v68, v69
	v_lshlrev_b32_e32 v68, 16, v136
	v_fmac_f32_e32 v76, v64, v68
	v_add_f32_e32 v64, 1.0, v65
	v_mul_f32_e32 v66, 0xbfb8aa3b, v66
	v_rcp_f32_e32 v64, v64
	v_exp_f32_e32 v66, v66
	v_mul_f32_e32 v67, 0xbfb8aa3b, v67
	v_exp_f32_e32 v67, v67
	v_and_b32_e32 v65, 0xffff0000, v136
	v_fmac_f32_e32 v77, v64, v65
	v_add_f32_e32 v64, 1.0, v66
	v_rcp_f32_e32 v64, v64
	v_add_f32_e32 v65, 1.0, v67
	v_rcp_f32_e32 v65, v65
	v_lshlrev_b32_e32 v66, 16, v137
	v_fmac_f32_e32 v78, v64, v66
	v_and_b32_e32 v64, 0xffff0000, v137
	v_fmac_f32_e32 v79, v65, v64
	v_lshlrev_b64 v[66:67], 12, v[134:135]
	v_cvt_pk_bf16_f32 v64, v76, v77
	v_cvt_pk_bf16_f32 v65, v78, v79
	v_lshl_add_u64 v[66:67], v[128:129], 0, v[66:67]
	global_store_dwordx2 v[66:67], v[64:65], off
	v_mul_f32_e32 v61, 0xbfb8aa3b, v61
	v_exp_f32_e32 v61, v61
	v_mul_f32_e32 v62, 0xbfb8aa3b, v62
	v_mul_f32_e32 v60, 0xbfb8aa3b, v60
	v_exp_f32_e32 v62, v62
	v_mul_f32_e32 v63, 0xbfb8aa3b, v63
	v_exp_f32_e32 v60, v60
	v_exp_f32_e32 v63, v63
	v_mul_f32_e32 v56, 0xbfb8aa3b, v56
	v_exp_f32_e32 v56, v56
	v_add_f32_e32 v61, 1.0, v61
	v_rcp_f32_e32 v61, v61
	v_add_f32_e32 v62, 1.0, v62
	v_add_f32_e32 v60, 1.0, v60
	v_rcp_f32_e32 v62, v62
	v_add_f32_e32 v63, 1.0, v63
	v_rcp_f32_e32 v60, v60
	v_rcp_f32_e32 v63, v63
	v_add_f32_e32 v56, 1.0, v56
	s_waitcnt vmcnt(0)
; __device__ __forceinline__ float lo16(unsigned u) { return __uint_as_float(u << 16); }
; __device__ __forceinline__ float hi16(unsigned u) { return __uint_as_float(u & 0xffff0000u); }
; __device__ __forceinline__ float sigm(float x) { return __builtin_amdgcn_rcpf(1.f + __expf(-x)); }
; __device__ __forceinline__ uint2 pack4(f32x4 a) { uint2 w; w.x = pack2(a[0], a[1]); w.y = pack2(a[2], a[3]); return w; }
; __global__ void __launch_bounds__(512) mega(Params p) {
;     ...
;             for (int m = 0; m < 4; ++m) {
;               f32x4 v = {0.f, 0.f, 0.f, 0.f};
; #pragma unroll
;               for (int bj = 0; bj < 2; ++bj)
; #pragma unroll
;                 for (int n = 0; n < 2; ++n) {
;                   uint2 y = yv[m][bj * 2 + n];
;                   f32x4 a = acc[ai][bj][m][n];
;                   v[0] += sigm(a[0]) * lo16(y.x); v[1] += sigm(a[1]) * hi16(y.x);
;                   v[2] += sigm(a[2]) * lo16(y.y); v[3] += sigm(a[3]) * hi16(y.y);
;                 }
;               *(uint2*)(MG + (rbase + m * 16) * 2048 + d0) = pack4(v);
	v_mov_b32_e32 v64, v182
	v_mov_b32_e32 v65, v183
	v_mov_b32_e32 v66, v184
	v_mov_b32_e32 v67, v185
	v_mov_b32_e32 v68, v186
	v_mov_b32_e32 v69, v187
	v_mov_b32_e32 v70, v188
	v_mov_b32_e32 v71, v189
	v_mov_b32_e32 v72, v190
	v_mov_b32_e32 v73, v191
	v_mov_b32_e32 v74, v192
	v_mov_b32_e32 v75, v193
	v_mov_b32_e32 v76, v194
	v_mov_b32_e32 v77, v195
	v_mov_b32_e32 v78, v196
	v_mov_b32_e32 v79, v197
	v_mov_b32_e32 v80, v198
	v_mov_b32_e32 v81, v199
	v_mov_b32_e32 v82, v200
	v_mov_b32_e32 v83, v201
	v_mov_b32_e32 v84, v202
	v_mov_b32_e32 v85, v203
	v_mov_b32_e32 v86, v204
	v_mov_b32_e32 v87, v205
	v_mov_b32_e32 v88, v206
	v_mov_b32_e32 v89, v207
	v_mov_b32_e32 v90, v208
	v_mov_b32_e32 v91, v209
	v_mov_b32_e32 v92, v210
	v_mov_b32_e32 v93, v211
	v_mov_b32_e32 v94, v212
	v_mov_b32_e32 v95, v213
	v_mov_b32_e32 v96, v214
	v_mov_b32_e32 v97, v215
	v_mov_b32_e32 v98, v216
	v_mov_b32_e32 v99, v217
	v_mov_b32_e32 v100, v218
	v_mov_b32_e32 v101, v219
	v_mov_b32_e32 v102, v222
	v_mov_b32_e32 v103, v223
	v_mov_b32_e32 v104, v224
	v_mov_b32_e32 v105, v225
	v_mov_b32_e32 v106, v226
	v_mov_b32_e32 v107, v227
	v_lshlrev_b32_e32 v104, 16, v98
	v_and_b32_e32 v98, 0xffff0000, v98
	v_rcp_f32_e32 v56, v56
	v_fma_f32 v61, v61, v98, 0
	v_lshlrev_b32_e32 v98, 16, v99
	v_fma_f32 v62, v62, v98, 0
	v_and_b32_e32 v98, 0xffff0000, v99
	v_fma_f32 v60, v60, v104, 0
	v_fma_f32 v63, v63, v98, 0
	v_lshlrev_b32_e32 v98, 16, v94
	v_mul_f32_e32 v57, 0xbfb8aa3b, v57
	v_exp_f32_e32 v57, v57
	v_fmac_f32_e32 v60, v56, v98
	v_mul_f32_e32 v56, 0xbfb8aa3b, v58
	v_exp_f32_e32 v56, v56
	v_add_f32_e32 v57, 1.0, v57
	v_rcp_f32_e32 v57, v57
	v_mul_f32_e32 v59, 0xbfb8aa3b, v59
	v_add_f32_e32 v56, 1.0, v56
	v_rcp_f32_e32 v56, v56
	v_exp_f32_e32 v59, v59
	v_mul_f32_e32 v52, 0xbfb8aa3b, v52
	v_exp_f32_e32 v52, v52
	v_mul_f32_e32 v53, 0xbfb8aa3b, v53
	v_and_b32_e32 v58, 0xffff0000, v94
	v_exp_f32_e32 v53, v53
	v_fmac_f32_e32 v61, v57, v58
	v_lshlrev_b32_e32 v57, 16, v95
	v_fmac_f32_e32 v62, v56, v57
	v_add_f32_e32 v56, 1.0, v59
	v_rcp_f32_e32 v56, v56
	v_add_f32_e32 v52, 1.0, v52
	v_rcp_f32_e32 v52, v52
	v_add_f32_e32 v53, 1.0, v53
	v_mul_f32_e32 v54, 0xbfb8aa3b, v54
	v_rcp_f32_e32 v53, v53
	v_exp_f32_e32 v54, v54
	v_and_b32_e32 v57, 0xffff0000, v95
	v_fmac_f32_e32 v63, v56, v57
	v_lshlrev_b32_e32 v56, 16, v96
	v_fmac_f32_e32 v60, v52, v56
	v_and_b32_e32 v52, 0xffff0000, v96
	v_fmac_f32_e32 v61, v53, v52
	v_add_f32_e32 v52, 1.0, v54
	v_mul_f32_e32 v54, 0xbfb8aa3b, v55
	v_rcp_f32_e32 v52, v52
	v_exp_f32_e32 v54, v54
	v_mul_f32_e32 v48, 0xbfb8aa3b, v48
	v_exp_f32_e32 v48, v48
	v_lshlrev_b32_e32 v53, 16, v97
	v_fmac_f32_e32 v62, v52, v53
	v_add_f32_e32 v52, 1.0, v54
	v_rcp_f32_e32 v52, v52
	v_add_f32_e32 v48, 1.0, v48
	v_mul_f32_e32 v49, 0xbfb8aa3b, v49
	v_rcp_f32_e32 v48, v48
	v_exp_f32_e32 v49, v49
	v_and_b32_e32 v53, 0xffff0000, v97
	v_fmac_f32_e32 v63, v52, v53
	v_lshlrev_b32_e32 v52, 16, v100
	v_fmac_f32_e32 v60, v48, v52
	v_add_f32_e32 v48, 1.0, v49
	v_mul_f32_e32 v50, 0xbfb8aa3b, v50
	v_rcp_f32_e32 v48, v48
	v_exp_f32_e32 v50, v50
	v_mul_f32_e32 v51, 0xbfb8aa3b, v51
	v_exp_f32_e32 v51, v51
	v_and_b32_e32 v49, 0xffff0000, v100
	v_mul_f32_e32 v44, 0xbfb8aa3b, v44
	v_fmac_f32_e32 v61, v48, v49
	v_add_f32_e32 v48, 1.0, v50
	v_exp_f32_e32 v44, v44
	v_mul_f32_e32 v45, 0xbfb8aa3b, v45
	v_rcp_f32_e32 v48, v48
	v_add_f32_e32 v49, 1.0, v51
	v_exp_f32_e32 v45, v45
	v_mul_f32_e32 v46, 0xbfb8aa3b, v46
	v_rcp_f32_e32 v49, v49
	v_exp_f32_e32 v46, v46
	v_mul_f32_e32 v47, 0xbfb8aa3b, v47
	v_exp_f32_e32 v47, v47
	v_mul_f32_e32 v40, 0xbfb8aa3b, v40
	v_lshlrev_b32_e32 v50, 16, v101
	v_add_f32_e32 v44, 1.0, v44
	v_exp_f32_e32 v40, v40
	v_fmac_f32_e32 v62, v48, v50
	v_and_b32_e32 v48, 0xffff0000, v101
	v_rcp_f32_e32 v44, v44
	v_add_f32_e32 v45, 1.0, v45
	v_fmac_f32_e32 v63, v49, v48
	v_lshlrev_b64 v[50:51], 12, v[92:93]
	v_rcp_f32_e32 v45, v45
	v_add_f32_e32 v46, 1.0, v46
	v_cvt_pk_bf16_f32 v48, v60, v61
	v_cvt_pk_bf16_f32 v49, v62, v63
	v_lshl_add_u64 v[50:51], v[128:129], 0, v[50:51]
	v_rcp_f32_e32 v46, v46
	v_add_f32_e32 v47, 1.0, v47
	global_store_dwordx2 v[50:51], v[48:49], off
	v_lshlrev_b32_e32 v48, 16, v102
	v_rcp_f32_e32 v47, v47
	v_add_f32_e32 v40, 1.0, v40
	v_fma_f32 v44, v44, v48, 0
	v_and_b32_e32 v48, 0xffff0000, v102
	v_rcp_f32_e32 v40, v40
	v_fma_f32 v45, v45, v48, 0
	v_lshlrev_b32_e32 v48, 16, v103
	v_fma_f32 v46, v46, v48, 0
	v_and_b32_e32 v48, 0xffff0000, v103
	v_fma_f32 v47, v47, v48, 0
	v_lshlrev_b32_e32 v48, 16, v90
	v_mul_f32_e32 v41, 0xbfb8aa3b, v41
	v_exp_f32_e32 v41, v41
	v_fmac_f32_e32 v44, v40, v48
	v_mul_f32_e32 v40, 0xbfb8aa3b, v42
	v_exp_f32_e32 v40, v40
	v_add_f32_e32 v41, 1.0, v41
	v_rcp_f32_e32 v41, v41
	v_mul_f32_e32 v43, 0xbfb8aa3b, v43
	v_add_f32_e32 v40, 1.0, v40
	v_rcp_f32_e32 v40, v40
	v_exp_f32_e32 v43, v43
	v_mul_f32_e32 v36, 0xbfb8aa3b, v36
	v_exp_f32_e32 v36, v36
	v_mul_f32_e32 v37, 0xbfb8aa3b, v37
	v_and_b32_e32 v42, 0xffff0000, v90
	v_exp_f32_e32 v37, v37
	v_fmac_f32_e32 v45, v41, v42
	v_lshlrev_b32_e32 v41, 16, v91
	v_fmac_f32_e32 v46, v40, v41
	v_add_f32_e32 v40, 1.0, v43
	v_rcp_f32_e32 v40, v40
	v_add_f32_e32 v36, 1.0, v36
	v_rcp_f32_e32 v36, v36
	v_add_f32_e32 v37, 1.0, v37
	v_mul_f32_e32 v38, 0xbfb8aa3b, v38
	v_rcp_f32_e32 v37, v37
	v_exp_f32_e32 v38, v38
	v_and_b32_e32 v41, 0xffff0000, v91
	v_fmac_f32_e32 v47, v40, v41
	v_lshlrev_b32_e32 v40, 16, v88
	v_fmac_f32_e32 v44, v36, v40
	v_and_b32_e32 v36, 0xffff0000, v88
	v_fmac_f32_e32 v45, v37, v36
	v_add_f32_e32 v36, 1.0, v38
	v_mul_f32_e32 v38, 0xbfb8aa3b, v39
	v_rcp_f32_e32 v36, v36
	v_exp_f32_e32 v38, v38
	v_mul_f32_e32 v32, 0xbfb8aa3b, v32
	v_exp_f32_e32 v32, v32
	v_lshlrev_b32_e32 v37, 16, v89
; __device__ __forceinline__ float lo16(unsigned u) { return __uint_as_float(u << 16); }
; __device__ __forceinline__ float hi16(unsigned u) { return __uint_as_float(u & 0xffff0000u); }
; __device__ __forceinline__ float sigm(float x) { return __builtin_amdgcn_rcpf(1.f + __expf(-x)); }
; #define SCHED __builtin_amdgcn_sched_barrier(0)
; __device__ __forceinline__ uint2 pack4(f32x4 a) { uint2 w; w.x = pack2(a[0], a[1]); w.y = pack2(a[2], a[3]); return w; }
; __global__ void __launch_bounds__(512) mega(Params p) {
;     ...
;             for (int m = 0; m < 4; ++m) {
;               f32x4 v = {0.f, 0.f, 0.f, 0.f};
; #pragma unroll
;               for (int bj = 0; bj < 2; ++bj)
; #pragma unroll
;                 for (int n = 0; n < 2; ++n) {
;                   uint2 y = yv[m][bj * 2 + n];
;                   f32x4 a = acc[ai][bj][m][n];
;                   v[0] += sigm(a[0]) * lo16(y.x); v[1] += sigm(a[1]) * hi16(y.x);
;                   v[2] += sigm(a[2]) * lo16(y.y); v[3] += sigm(a[3]) * hi16(y.y);
;                 }
;               *(uint2*)(MG + (rbase + m * 16) * 2048 + d0) = pack4(v);
;             }
;             SCHED;
	v_fmac_f32_e32 v46, v36, v37
	v_add_f32_e32 v36, 1.0, v38
	v_rcp_f32_e32 v36, v36
	v_add_f32_e32 v32, 1.0, v32
	v_mul_f32_e32 v33, 0xbfb8aa3b, v33
	v_rcp_f32_e32 v32, v32
	v_exp_f32_e32 v33, v33
	v_and_b32_e32 v37, 0xffff0000, v89
	v_fmac_f32_e32 v47, v36, v37
	v_lshlrev_b32_e32 v36, 16, v86
	v_fmac_f32_e32 v44, v32, v36
	v_add_f32_e32 v32, 1.0, v33
	v_mul_f32_e32 v34, 0xbfb8aa3b, v34
	v_rcp_f32_e32 v32, v32
	v_exp_f32_e32 v34, v34
	v_mul_f32_e32 v35, 0xbfb8aa3b, v35
	v_exp_f32_e32 v35, v35
	v_and_b32_e32 v33, 0xffff0000, v86
	v_mul_f32_e32 v28, 0xbfb8aa3b, v28
	v_fmac_f32_e32 v45, v32, v33
	v_add_f32_e32 v32, 1.0, v34
	v_exp_f32_e32 v28, v28
	v_mul_f32_e32 v29, 0xbfb8aa3b, v29
	v_rcp_f32_e32 v32, v32
	v_add_f32_e32 v33, 1.0, v35
	v_exp_f32_e32 v29, v29
	v_mul_f32_e32 v30, 0xbfb8aa3b, v30
	v_rcp_f32_e32 v33, v33
	v_exp_f32_e32 v30, v30
	v_mul_f32_e32 v31, 0xbfb8aa3b, v31
	v_exp_f32_e32 v31, v31
	v_mul_f32_e32 v24, 0xbfb8aa3b, v24
	v_lshlrev_b32_e32 v34, 16, v87
	v_add_f32_e32 v28, 1.0, v28
	v_exp_f32_e32 v24, v24
	v_fmac_f32_e32 v46, v32, v34
	v_and_b32_e32 v32, 0xffff0000, v87
	v_rcp_f32_e32 v28, v28
	v_add_f32_e32 v29, 1.0, v29
	v_fmac_f32_e32 v47, v33, v32
	v_lshlrev_b64 v[34:35], 12, v[82:83]
	v_rcp_f32_e32 v29, v29
	v_add_f32_e32 v30, 1.0, v30
	v_cvt_pk_bf16_f32 v32, v44, v45
	v_cvt_pk_bf16_f32 v33, v46, v47
	v_lshl_add_u64 v[34:35], v[128:129], 0, v[34:35]
	v_rcp_f32_e32 v30, v30
	v_add_f32_e32 v31, 1.0, v31
	global_store_dwordx2 v[34:35], v[32:33], off
	v_lshlrev_b32_e32 v32, 16, v84
	v_rcp_f32_e32 v31, v31
	v_add_f32_e32 v24, 1.0, v24
	v_fma_f32 v28, v28, v32, 0
	v_and_b32_e32 v32, 0xffff0000, v84
	v_rcp_f32_e32 v24, v24
	v_fma_f32 v29, v29, v32, 0
	v_lshlrev_b32_e32 v32, 16, v85
	v_fma_f32 v30, v30, v32, 0
	v_and_b32_e32 v32, 0xffff0000, v85
	v_fma_f32 v31, v31, v32, 0
	v_lshlrev_b32_e32 v32, 16, v80
	v_mul_f32_e32 v25, 0xbfb8aa3b, v25
	v_exp_f32_e32 v25, v25
	v_fmac_f32_e32 v28, v24, v32
	v_mul_f32_e32 v24, 0xbfb8aa3b, v26
	v_exp_f32_e32 v24, v24
	v_add_f32_e32 v25, 1.0, v25
	v_rcp_f32_e32 v25, v25
	v_mul_f32_e32 v27, 0xbfb8aa3b, v27
	v_add_f32_e32 v24, 1.0, v24
	v_rcp_f32_e32 v24, v24
	v_exp_f32_e32 v27, v27
	v_mul_f32_e32 v20, 0xbfb8aa3b, v20
	v_exp_f32_e32 v20, v20
	v_mul_f32_e32 v21, 0xbfb8aa3b, v21
	v_and_b32_e32 v26, 0xffff0000, v80
	v_exp_f32_e32 v21, v21
	v_fmac_f32_e32 v29, v25, v26
	v_lshlrev_b32_e32 v25, 16, v81
	v_fmac_f32_e32 v30, v24, v25
	v_add_f32_e32 v24, 1.0, v27
	v_rcp_f32_e32 v24, v24
	v_add_f32_e32 v20, 1.0, v20
	v_rcp_f32_e32 v20, v20
	v_add_f32_e32 v21, 1.0, v21
	v_mul_f32_e32 v22, 0xbfb8aa3b, v22
	v_rcp_f32_e32 v21, v21
	v_exp_f32_e32 v22, v22
	v_and_b32_e32 v25, 0xffff0000, v81
	v_fmac_f32_e32 v31, v24, v25
	v_lshlrev_b32_e32 v24, 16, v78
	v_fmac_f32_e32 v28, v20, v24
	v_and_b32_e32 v20, 0xffff0000, v78
	v_fmac_f32_e32 v29, v21, v20
	v_add_f32_e32 v20, 1.0, v22
	v_mul_f32_e32 v22, 0xbfb8aa3b, v23
	v_rcp_f32_e32 v20, v20
	v_exp_f32_e32 v22, v22
	v_mul_f32_e32 v16, 0xbfb8aa3b, v16
	v_exp_f32_e32 v16, v16
	v_lshlrev_b32_e32 v21, 16, v79
	v_fmac_f32_e32 v30, v20, v21
	v_add_f32_e32 v20, 1.0, v22
	v_rcp_f32_e32 v20, v20
	v_add_f32_e32 v16, 1.0, v16
	v_mul_f32_e32 v17, 0xbfb8aa3b, v17
	v_rcp_f32_e32 v16, v16
	v_exp_f32_e32 v17, v17
	v_and_b32_e32 v21, 0xffff0000, v79
	v_fmac_f32_e32 v31, v20, v21
	v_lshlrev_b32_e32 v20, 16, v76
	v_fmac_f32_e32 v28, v16, v20
	v_add_f32_e32 v16, 1.0, v17
	v_mul_f32_e32 v18, 0xbfb8aa3b, v18
	v_rcp_f32_e32 v16, v16
	v_exp_f32_e32 v18, v18
	v_mul_f32_e32 v19, 0xbfb8aa3b, v19
	v_exp_f32_e32 v19, v19
	v_and_b32_e32 v17, 0xffff0000, v76
	v_mul_f32_e32 v12, 0xbfb8aa3b, v12
	v_fmac_f32_e32 v29, v16, v17
	v_add_f32_e32 v16, 1.0, v18
	v_exp_f32_e32 v12, v12
	v_mul_f32_e32 v13, 0xbfb8aa3b, v13
	v_rcp_f32_e32 v16, v16
	v_add_f32_e32 v17, 1.0, v19
	v_exp_f32_e32 v13, v13
	v_mul_f32_e32 v14, 0xbfb8aa3b, v14
	v_rcp_f32_e32 v17, v17
	v_exp_f32_e32 v14, v14
	v_mul_f32_e32 v15, 0xbfb8aa3b, v15
	v_exp_f32_e32 v15, v15
	v_mul_f32_e32 v8, 0xbfb8aa3b, v8
	v_lshlrev_b32_e32 v18, 16, v77
	v_add_f32_e32 v12, 1.0, v12
	v_exp_f32_e32 v8, v8
	v_fmac_f32_e32 v30, v16, v18
	v_and_b32_e32 v16, 0xffff0000, v77
	v_rcp_f32_e32 v12, v12
	v_add_f32_e32 v13, 1.0, v13
	v_fmac_f32_e32 v31, v17, v16
	v_lshlrev_b64 v[18:19], 12, v[72:73]
	v_rcp_f32_e32 v13, v13
	v_add_f32_e32 v14, 1.0, v14
	v_cvt_pk_bf16_f32 v16, v28, v29
	v_cvt_pk_bf16_f32 v17, v30, v31
	v_lshl_add_u64 v[18:19], v[128:129], 0, v[18:19]
	v_rcp_f32_e32 v14, v14
	v_add_f32_e32 v15, 1.0, v15
	global_store_dwordx2 v[18:19], v[16:17], off
	v_lshlrev_b32_e32 v16, 16, v74
	v_rcp_f32_e32 v15, v15
	v_add_f32_e32 v8, 1.0, v8
	v_fma_f32 v12, v12, v16, 0
	v_and_b32_e32 v16, 0xffff0000, v74
	v_rcp_f32_e32 v8, v8
	v_fma_f32 v13, v13, v16, 0
	v_lshlrev_b32_e32 v16, 16, v75
	v_fma_f32 v14, v14, v16, 0
	v_and_b32_e32 v16, 0xffff0000, v75
	v_fma_f32 v15, v15, v16, 0
	v_lshlrev_b32_e32 v16, 16, v70
	v_mul_f32_e32 v9, 0xbfb8aa3b, v9
	v_exp_f32_e32 v9, v9
	v_fmac_f32_e32 v12, v8, v16
	v_mul_f32_e32 v8, 0xbfb8aa3b, v10
	v_exp_f32_e32 v8, v8
	v_add_f32_e32 v9, 1.0, v9
	v_rcp_f32_e32 v9, v9
	v_mul_f32_e32 v11, 0xbfb8aa3b, v11
	v_add_f32_e32 v8, 1.0, v8
	v_rcp_f32_e32 v8, v8
	v_exp_f32_e32 v11, v11
	v_mul_f32_e32 v4, 0xbfb8aa3b, v4
	v_exp_f32_e32 v4, v4
	v_mul_f32_e32 v5, 0xbfb8aa3b, v5
	v_and_b32_e32 v10, 0xffff0000, v70
	v_exp_f32_e32 v5, v5
	v_fmac_f32_e32 v13, v9, v10
	v_lshlrev_b32_e32 v9, 16, v71
	v_fmac_f32_e32 v14, v8, v9
	v_add_f32_e32 v8, 1.0, v11
	v_rcp_f32_e32 v8, v8
	v_add_f32_e32 v4, 1.0, v4
	v_rcp_f32_e32 v4, v4
	v_add_f32_e32 v5, 1.0, v5
	v_mul_f32_e32 v6, 0xbfb8aa3b, v6
	v_rcp_f32_e32 v5, v5
	v_exp_f32_e32 v6, v6
	v_and_b32_e32 v9, 0xffff0000, v71
	v_fmac_f32_e32 v15, v8, v9
	v_lshlrev_b32_e32 v8, 16, v68
	v_fmac_f32_e32 v12, v4, v8
	v_and_b32_e32 v4, 0xffff0000, v68
	v_fmac_f32_e32 v13, v5, v4
	v_add_f32_e32 v4, 1.0, v6
	v_mul_f32_e32 v6, 0xbfb8aa3b, v7
	v_rcp_f32_e32 v4, v4
	v_exp_f32_e32 v6, v6
	v_mul_f32_e32 v0, 0xbfb8aa3b, v0
	v_exp_f32_e32 v0, v0
	v_lshlrev_b32_e32 v5, 16, v69
	v_fmac_f32_e32 v14, v4, v5
	v_add_f32_e32 v4, 1.0, v6
	v_rcp_f32_e32 v4, v4
	v_add_f32_e32 v0, 1.0, v0
	v_mul_f32_e32 v1, 0xbfb8aa3b, v1
	v_rcp_f32_e32 v0, v0
	v_exp_f32_e32 v1, v1
	v_and_b32_e32 v5, 0xffff0000, v69
	v_fmac_f32_e32 v15, v4, v5
	v_lshlrev_b32_e32 v4, 16, v66
	v_fmac_f32_e32 v12, v0, v4
	v_add_f32_e32 v0, 1.0, v1
	v_mul_f32_e32 v2, 0xbfb8aa3b, v2
	v_rcp_f32_e32 v0, v0
	v_exp_f32_e32 v2, v2
	v_mul_f32_e32 v3, 0xbfb8aa3b, v3
	v_exp_f32_e32 v3, v3
	v_and_b32_e32 v1, 0xffff0000, v66
	v_fmac_f32_e32 v13, v0, v1
	v_add_f32_e32 v0, 1.0, v2
	v_rcp_f32_e32 v0, v0
	v_add_f32_e32 v1, 1.0, v3
	v_rcp_f32_e32 v1, v1
	v_lshlrev_b32_e32 v2, 16, v67
	v_fmac_f32_e32 v14, v0, v2
	v_and_b32_e32 v0, 0xffff0000, v67
	v_fmac_f32_e32 v15, v1, v0
	v_lshlrev_b64 v[2:3], 12, v[64:65]
	v_cvt_pk_bf16_f32 v0, v12, v13
	v_cvt_pk_bf16_f32 v1, v14, v15
	v_lshl_add_u64 v[2:3], v[128:129], 0, v[2:3]
	global_store_dwordx2 v[2:3], v[0:1], off
	s_andn2_b64 vcc, exec, s[20:21]
	s_mov_b32 s18, s24
	s_mov_b32 s14, s22
	s_cbranch_vccz .LBB0_2522
